# grid barrier: the acquire L1 invalidate (buffer_inv sc1) issued before the spin / next to the leader's wbl2 instead of after the release is seen (no L1-allocating load in between)
# speedup vs baseline: 1.0120x; 1.0120x over previous
; __device__ __forceinline__ unsigned xb_ld(unsigned* p)              { return __hip_atomic_load(p, __ATOMIC_RELAXED, __HIP_MEMORY_SCOPE_AGENT); }
; __device__ __forceinline__ unsigned xb_add(unsigned* p, unsigned v) { return __hip_atomic_fetch_add(p, v, __ATOMIC_RELAXED, __HIP_MEMORY_SCOPE_AGENT); }
; #define XB_SPIN(cond, bar) do { unsigned _sp = 0; while (cond) { \
;     if ((++_sp & 255u) == 0u) { if (xb_ld(&(bar)[XB_TMO])) break; if (_sp > XB_SPIN_CAP) { atomicAdd(&(bar)[XB_TMO], 1u); break; } } } } while (0)
; __device__ __forceinline__ void xcd_barrier(unsigned* barw, volatile LAS unsigned* stw, const int wv) {
;     ...
;         const unsigned old = xb_add(&bar[XB_XSUB(b.x)], 1u);
;         const unsigned gen = old / nloc;
;         if (old + 1u == (gen + 1u) * nloc) {
;             __builtin_amdgcn_fence(__ATOMIC_RELEASE, "agent");
;             asm volatile("s_waitcnt vmcnt(0)" ::: "memory");
;             const unsigned og = xb_add(&bar[XB_TOP], 1u);
;             const unsigned tg = og / nx;
;             if (og + 1u == (tg + 1u) * nx) xb_add(&bar[XB_TOPGEN], 1u);
;             else XB_SPIN(xb_ld(&bar[XB_TOPGEN]) == tg, bar);
;             __builtin_amdgcn_fence(__ATOMIC_ACQUIRE, "agent");
;             xb_add(&bar[XB_XGEN(b.x)], 1u);
;             asm volatile("s_waitcnt vmcnt(0)" ::: "memory");
;         } else {
;             XB_SPIN(xb_ld(&bar[XB_XGEN(b.x)]) == gen, bar);
.LBB0_113:
	s_or_b64 exec, exec, s[18:19]
	v_cvt_f32_u32_e32 v4, v2
	s_waitcnt vmcnt(0)
	v_readfirstlane_b32 s3, v3
	v_sub_u32_e32 v3, 0, v2
	v_rcp_iflag_f32_e32 v4, v4
	v_add_u32_e32 v5, s3, v1
	v_mul_f32_e32 v4, 0x4f7ffffe, v4
	v_cvt_u32_f32_e32 v4, v4
	v_mul_lo_u32 v1, v3, v4
	v_mul_hi_u32 v1, v4, v1
	v_add_u32_e32 v1, v4, v1
	v_mul_hi_u32 v1, v5, v1
	v_mul_lo_u32 v3, v1, v2
	v_sub_u32_e32 v3, v5, v3
	v_add_u32_e32 v4, 1, v1
	v_cmp_ge_u32_e32 vcc, v3, v2
	s_nop 1
	v_cndmask_b32_e32 v1, v1, v4, vcc
	v_sub_u32_e32 v4, v3, v2
	v_cndmask_b32_e32 v3, v3, v4, vcc
	v_add_u32_e32 v4, 1, v1
	v_cmp_ge_u32_e32 vcc, v3, v2
	v_add_u32_e32 v3, 1, v5
	s_nop 0
	v_cndmask_b32_e32 v1, v1, v4, vcc
	v_mul_lo_u32 v4, v2, v1
	v_add_u32_e32 v2, v4, v2
	v_cmp_ne_u32_e32 vcc, v3, v2
	s_and_saveexec_b64 s[4:5], vcc
	s_xor_b64 s[16:17], exec, s[4:5]
	s_cbranch_execz .LBB0_127
	s_waitcnt lgkmcnt(0)
	buffer_inv sc1
	v_mov_b32_e32 v0, 0x3100
	global_load_dword v0, v0, s[12:13] offset:1024 sc1
	s_add_u32 s20, s12, 0x3500
	s_addc_u32 s21, s13, 0
	s_waitcnt vmcnt(0)
	v_cmp_eq_u32_e32 vcc, v0, v1
	s_and_saveexec_b64 s[18:19], vcc
	s_cbranch_execz .LBB0_126
	s_mov_b32 s3, 1
	s_mov_b64 s[22:23], 0
	v_mov_b32_e32 v0, 0
	s_branch .LBB0_117

; __device__ __forceinline__ unsigned xb_ld(unsigned* p)              { return __hip_atomic_load(p, __ATOMIC_RELAXED, __HIP_MEMORY_SCOPE_AGENT); }
; __device__ __forceinline__ unsigned xb_add(unsigned* p, unsigned v) { return __hip_atomic_fetch_add(p, v, __ATOMIC_RELAXED, __HIP_MEMORY_SCOPE_AGENT); }
; #define XB_SPIN(cond, bar) do { unsigned _sp = 0; while (cond) { \
;     if ((++_sp & 255u) == 0u) { if (xb_ld(&(bar)[XB_TMO])) break; if (_sp > XB_SPIN_CAP) { atomicAdd(&(bar)[XB_TMO], 1u); break; } } } } while (0)
; __device__ __forceinline__ void xcd_barrier(unsigned* barw, volatile LAS unsigned* stw, const int wv) {
;     ...
;         if (old + 1u == (gen + 1u) * nloc) {
;             __builtin_amdgcn_fence(__ATOMIC_RELEASE, "agent");
;             asm volatile("s_waitcnt vmcnt(0)" ::: "memory");
;             const unsigned og = xb_add(&bar[XB_TOP], 1u);
;             const unsigned tg = og / nx;
;             if (og + 1u == (tg + 1u) * nx) xb_add(&bar[XB_TOPGEN], 1u);
;             else XB_SPIN(xb_ld(&bar[XB_TOPGEN]) == tg, bar);
;             __builtin_amdgcn_fence(__ATOMIC_ACQUIRE, "agent");
;             xb_add(&bar[XB_XGEN(b.x)], 1u);
;             asm volatile("s_waitcnt vmcnt(0)" ::: "memory");
;         } else {
;             XB_SPIN(xb_ld(&bar[XB_XGEN(b.x)]) == gen, bar);
;             __builtin_amdgcn_fence(__ATOMIC_ACQUIRE, "agent");
;             asm volatile("s_waitcnt vmcnt(0)" ::: "memory");
.LBB0_126:
	s_or_b64 exec, exec, s[18:19]
	s_waitcnt vmcnt(0)
	s_waitcnt vmcnt(0)
.LBB0_127:
	s_andn2_saveexec_b64 s[4:5], s[16:17]
	s_cbranch_execz .LBB0_147
	s_mov_b64 s[16:17], exec
	buffer_wbl2 sc1
	buffer_inv sc1
	s_waitcnt lgkmcnt(0)
	s_waitcnt vmcnt(0)
	v_mbcnt_lo_u32_b32 v1, s16, 0
	v_mbcnt_hi_u32_b32 v1, s17, v1
	v_cmp_eq_u32_e32 vcc, 0, v1
	s_and_saveexec_b64 s[18:19], vcc
	s_cbranch_execz .LBB0_130
	s_bcnt1_i32_b64 s3, s[16:17]
	v_mov_b32_e32 v2, 0x3000
	v_mov_b32_e32 v3, s3
	global_atomic_add v2, v2, v3, s[12:13] offset:1024 sc0

; __device__ __forceinline__ unsigned xb_ld(unsigned* p)              { return __hip_atomic_load(p, __ATOMIC_RELAXED, __HIP_MEMORY_SCOPE_AGENT); }
; __device__ __forceinline__ unsigned xb_add(unsigned* p, unsigned v) { return __hip_atomic_fetch_add(p, v, __ATOMIC_RELAXED, __HIP_MEMORY_SCOPE_AGENT); }
; #define XB_SPIN(cond, bar) do { unsigned _sp = 0; while (cond) { \
;     if ((++_sp & 255u) == 0u) { if (xb_ld(&(bar)[XB_TMO])) break; if (_sp > XB_SPIN_CAP) { atomicAdd(&(bar)[XB_TMO], 1u); break; } } } } while (0)
; __device__ __forceinline__ void xcd_barrier(unsigned* barw, volatile LAS unsigned* stw, const int wv) {
;     ...
;             else XB_SPIN(xb_ld(&bar[XB_TOPGEN]) == tg, bar);
;             __builtin_amdgcn_fence(__ATOMIC_ACQUIRE, "agent");
;             xb_add(&bar[XB_XGEN(b.x)], 1u);
;             asm volatile("s_waitcnt vmcnt(0)" ::: "memory");
.LBB0_144:
	s_or_b64 exec, exec, s[10:11]
	s_mov_b64 s[10:11], exec
	v_mbcnt_lo_u32_b32 v0, s10, 0
	v_mbcnt_hi_u32_b32 v0, s11, v0
	v_cmp_eq_u32_e32 vcc, 0, v0
	s_waitcnt vmcnt(0)
	s_and_saveexec_b64 s[12:13], vcc
	s_cbranch_execz .LBB0_146

; __device__ __forceinline__ unsigned xb_ld(unsigned* p)              { return __hip_atomic_load(p, __ATOMIC_RELAXED, __HIP_MEMORY_SCOPE_AGENT); }
; __device__ __forceinline__ unsigned xb_add(unsigned* p, unsigned v) { return __hip_atomic_fetch_add(p, v, __ATOMIC_RELAXED, __HIP_MEMORY_SCOPE_AGENT); }
; #define XB_SPIN(cond, bar) do { unsigned _sp = 0; while (cond) { \
;     if ((++_sp & 255u) == 0u) { if (xb_ld(&(bar)[XB_TMO])) break; if (_sp > XB_SPIN_CAP) { atomicAdd(&(bar)[XB_TMO], 1u); break; } } } } while (0)
; __device__ __forceinline__ void xcd_barrier(unsigned* barw, volatile LAS unsigned* stw, const int wv) {
;     ...
;         const unsigned old = xb_add(&bar[XB_XSUB(b.x)], 1u);
;         const unsigned gen = old / nloc;
;         if (old + 1u == (gen + 1u) * nloc) {
;             __builtin_amdgcn_fence(__ATOMIC_RELEASE, "agent");
;             asm volatile("s_waitcnt vmcnt(0)" ::: "memory");
;             const unsigned og = xb_add(&bar[XB_TOP], 1u);
;             const unsigned tg = og / nx;
;             if (og + 1u == (tg + 1u) * nx) xb_add(&bar[XB_TOPGEN], 1u);
;             else XB_SPIN(xb_ld(&bar[XB_TOPGEN]) == tg, bar);
;             __builtin_amdgcn_fence(__ATOMIC_ACQUIRE, "agent");
;             xb_add(&bar[XB_XGEN(b.x)], 1u);
;             asm volatile("s_waitcnt vmcnt(0)" ::: "memory");
;         } else {
;             XB_SPIN(xb_ld(&bar[XB_XGEN(b.x)]) == gen, bar);
.LBB0_181:
	s_or_b64 exec, exec, s[18:19]
	v_cvt_f32_u32_e32 v4, v2
	s_waitcnt vmcnt(0)
	v_readfirstlane_b32 s4, v3
	v_sub_u32_e32 v3, 0, v2
	v_rcp_iflag_f32_e32 v4, v4
	v_add_u32_e32 v5, s4, v1
	v_mul_f32_e32 v4, 0x4f7ffffe, v4
	v_cvt_u32_f32_e32 v4, v4
	v_mul_lo_u32 v1, v3, v4
	v_mul_hi_u32 v1, v4, v1
	v_add_u32_e32 v1, v4, v1
	v_mul_hi_u32 v1, v5, v1
	v_mul_lo_u32 v3, v1, v2
	v_sub_u32_e32 v3, v5, v3
	v_add_u32_e32 v4, 1, v1
	v_cmp_ge_u32_e32 vcc, v3, v2
	s_nop 1
	v_cndmask_b32_e32 v1, v1, v4, vcc
	v_sub_u32_e32 v4, v3, v2
	v_cndmask_b32_e32 v3, v3, v4, vcc
	v_add_u32_e32 v4, 1, v1
	v_cmp_ge_u32_e32 vcc, v3, v2
	v_add_u32_e32 v3, 1, v5
	s_nop 0
	v_cndmask_b32_e32 v1, v1, v4, vcc
	v_mul_lo_u32 v4, v2, v1
	v_add_u32_e32 v2, v4, v2
	v_cmp_ne_u32_e32 vcc, v3, v2
	s_and_saveexec_b64 s[4:5], vcc
	s_xor_b64 s[16:17], exec, s[4:5]
	s_cbranch_execz .LBB0_195
	s_waitcnt lgkmcnt(0)
	buffer_inv sc1
	v_mov_b32_e32 v0, 0x3100
	global_load_dword v0, v0, s[10:11] offset:1024 sc1
	s_add_u32 s20, s10, 0x3500
	s_addc_u32 s21, s11, 0
	s_waitcnt vmcnt(0)
	v_cmp_eq_u32_e32 vcc, v0, v1
	s_and_saveexec_b64 s[18:19], vcc
	s_cbranch_execz .LBB0_194
	s_mov_b32 s4, 1
	s_mov_b64 s[22:23], 0
	v_mov_b32_e32 v0, 0
	s_branch .LBB0_185

; __device__ __forceinline__ unsigned xb_ld(unsigned* p)              { return __hip_atomic_load(p, __ATOMIC_RELAXED, __HIP_MEMORY_SCOPE_AGENT); }
; __device__ __forceinline__ unsigned xb_add(unsigned* p, unsigned v) { return __hip_atomic_fetch_add(p, v, __ATOMIC_RELAXED, __HIP_MEMORY_SCOPE_AGENT); }
; #define XB_SPIN(cond, bar) do { unsigned _sp = 0; while (cond) { \
;     if ((++_sp & 255u) == 0u) { if (xb_ld(&(bar)[XB_TMO])) break; if (_sp > XB_SPIN_CAP) { atomicAdd(&(bar)[XB_TMO], 1u); break; } } } } while (0)
; __device__ __forceinline__ void xcd_barrier(unsigned* barw, volatile LAS unsigned* stw, const int wv) {
;     ...
;         if (old + 1u == (gen + 1u) * nloc) {
;             __builtin_amdgcn_fence(__ATOMIC_RELEASE, "agent");
;             asm volatile("s_waitcnt vmcnt(0)" ::: "memory");
;             const unsigned og = xb_add(&bar[XB_TOP], 1u);
;             const unsigned tg = og / nx;
;             if (og + 1u == (tg + 1u) * nx) xb_add(&bar[XB_TOPGEN], 1u);
;             else XB_SPIN(xb_ld(&bar[XB_TOPGEN]) == tg, bar);
.LBB0_195:
	s_andn2_saveexec_b64 s[4:5], s[16:17]
	s_cbranch_execz .LBB0_215
	s_mov_b64 s[16:17], exec
	buffer_wbl2 sc1
	buffer_inv sc1
	s_waitcnt lgkmcnt(0)
	s_waitcnt vmcnt(0)
	v_mbcnt_lo_u32_b32 v1, s16, 0
	v_mbcnt_hi_u32_b32 v1, s17, v1
	v_cmp_eq_u32_e32 vcc, 0, v1
	s_and_saveexec_b64 s[18:19], vcc
	s_cbranch_execz .LBB0_198
	s_bcnt1_i32_b64 s4, s[16:17]
	v_mov_b32_e32 v2, 0x3000
	v_mov_b32_e32 v3, s4
	global_atomic_add v2, v2, v3, s[10:11] offset:1024 sc0

; __device__ __forceinline__ unsigned xb_ld(unsigned* p)              { return __hip_atomic_load(p, __ATOMIC_RELAXED, __HIP_MEMORY_SCOPE_AGENT); }
; __device__ __forceinline__ unsigned xb_add(unsigned* p, unsigned v) { return __hip_atomic_fetch_add(p, v, __ATOMIC_RELAXED, __HIP_MEMORY_SCOPE_AGENT); }
; #define XB_SPIN(cond, bar) do { unsigned _sp = 0; while (cond) { \
;     if ((++_sp & 255u) == 0u) { if (xb_ld(&(bar)[XB_TMO])) break; if (_sp > XB_SPIN_CAP) { atomicAdd(&(bar)[XB_TMO], 1u); break; } } } } while (0)
; __device__ __forceinline__ void xcd_barrier(unsigned* barw, volatile LAS unsigned* stw, const int wv) {
;     ...
;         const unsigned old = xb_add(&bar[XB_XSUB(b.x)], 1u);
;         const unsigned gen = old / nloc;
;         if (old + 1u == (gen + 1u) * nloc) {
;             __builtin_amdgcn_fence(__ATOMIC_RELEASE, "agent");
;             asm volatile("s_waitcnt vmcnt(0)" ::: "memory");
;             const unsigned og = xb_add(&bar[XB_TOP], 1u);
;             const unsigned tg = og / nx;
;             if (og + 1u == (tg + 1u) * nx) xb_add(&bar[XB_TOPGEN], 1u);
;             else XB_SPIN(xb_ld(&bar[XB_TOPGEN]) == tg, bar);
;             __builtin_amdgcn_fence(__ATOMIC_ACQUIRE, "agent");
;             xb_add(&bar[XB_XGEN(b.x)], 1u);
;             asm volatile("s_waitcnt vmcnt(0)" ::: "memory");
;         } else {
;             XB_SPIN(xb_ld(&bar[XB_XGEN(b.x)]) == gen, bar);
.LBB0_325:
	s_or_b64 exec, exec, s[18:19]
	v_cvt_f32_u32_e32 v4, v2
	s_waitcnt vmcnt(0)
	v_readfirstlane_b32 s4, v3
	v_sub_u32_e32 v3, 0, v2
	v_rcp_iflag_f32_e32 v4, v4
	v_add_u32_e32 v5, s4, v1
	v_mul_f32_e32 v4, 0x4f7ffffe, v4
	v_cvt_u32_f32_e32 v4, v4
	v_mul_lo_u32 v1, v3, v4
	v_mul_hi_u32 v1, v4, v1
	v_add_u32_e32 v1, v4, v1
	v_mul_hi_u32 v1, v5, v1
	v_mul_lo_u32 v3, v1, v2
	v_sub_u32_e32 v3, v5, v3
	v_add_u32_e32 v4, 1, v1
	v_cmp_ge_u32_e32 vcc, v3, v2
	s_nop 1
	v_cndmask_b32_e32 v1, v1, v4, vcc
	v_sub_u32_e32 v4, v3, v2
	v_cndmask_b32_e32 v3, v3, v4, vcc
	v_add_u32_e32 v4, 1, v1
	v_cmp_ge_u32_e32 vcc, v3, v2
	v_add_u32_e32 v3, 1, v5
	s_nop 0
	v_cndmask_b32_e32 v1, v1, v4, vcc
	v_mul_lo_u32 v4, v2, v1
	v_add_u32_e32 v2, v4, v2
	v_cmp_ne_u32_e32 vcc, v3, v2
	s_and_saveexec_b64 s[4:5], vcc
	s_xor_b64 s[16:17], exec, s[4:5]
	s_cbranch_execz .LBB0_339
	s_waitcnt lgkmcnt(0)
	buffer_inv sc1
	v_mov_b32_e32 v0, 0x3100
	global_load_dword v0, v0, s[14:15] offset:1024 sc1
	s_add_u32 s20, s14, 0x3500
	s_addc_u32 s21, s15, 0
	s_waitcnt vmcnt(0)
	v_cmp_eq_u32_e32 vcc, v0, v1
	s_and_saveexec_b64 s[18:19], vcc
	s_cbranch_execz .LBB0_338
	s_mov_b32 s4, 1
	s_mov_b64 s[22:23], 0
	v_mov_b32_e32 v0, 0
	s_branch .LBB0_329

; __device__ __forceinline__ unsigned xb_ld(unsigned* p)              { return __hip_atomic_load(p, __ATOMIC_RELAXED, __HIP_MEMORY_SCOPE_AGENT); }
; __device__ __forceinline__ unsigned xb_add(unsigned* p, unsigned v) { return __hip_atomic_fetch_add(p, v, __ATOMIC_RELAXED, __HIP_MEMORY_SCOPE_AGENT); }
; #define XB_SPIN(cond, bar) do { unsigned _sp = 0; while (cond) { \
;     if ((++_sp & 255u) == 0u) { if (xb_ld(&(bar)[XB_TMO])) break; if (_sp > XB_SPIN_CAP) { atomicAdd(&(bar)[XB_TMO], 1u); break; } } } } while (0)
; __device__ __forceinline__ void xcd_barrier(unsigned* barw, volatile LAS unsigned* stw, const int wv) {
;     ...
;         if (old + 1u == (gen + 1u) * nloc) {
;             __builtin_amdgcn_fence(__ATOMIC_RELEASE, "agent");
;             asm volatile("s_waitcnt vmcnt(0)" ::: "memory");
;             const unsigned og = xb_add(&bar[XB_TOP], 1u);
;             const unsigned tg = og / nx;
;             if (og + 1u == (tg + 1u) * nx) xb_add(&bar[XB_TOPGEN], 1u);
;             else XB_SPIN(xb_ld(&bar[XB_TOPGEN]) == tg, bar);
.LBB0_339:
	s_andn2_saveexec_b64 s[4:5], s[16:17]
	s_cbranch_execz .LBB0_359
	s_mov_b64 s[16:17], exec
	buffer_wbl2 sc1
	buffer_inv sc1
	s_waitcnt lgkmcnt(0)
	s_waitcnt vmcnt(0)
	v_mbcnt_lo_u32_b32 v1, s16, 0
	v_mbcnt_hi_u32_b32 v1, s17, v1
	v_cmp_eq_u32_e32 vcc, 0, v1
	s_and_saveexec_b64 s[18:19], vcc
	s_cbranch_execz .LBB0_342
	s_bcnt1_i32_b64 s4, s[16:17]
	v_mov_b32_e32 v2, 0x3000
	v_mov_b32_e32 v3, s4
	global_atomic_add v2, v2, v3, s[14:15] offset:1024 sc0

; __device__ __forceinline__ unsigned xb_ld(unsigned* p)              { return __hip_atomic_load(p, __ATOMIC_RELAXED, __HIP_MEMORY_SCOPE_AGENT); }
; __device__ __forceinline__ unsigned xb_add(unsigned* p, unsigned v) { return __hip_atomic_fetch_add(p, v, __ATOMIC_RELAXED, __HIP_MEMORY_SCOPE_AGENT); }
; #define XB_SPIN(cond, bar) do { unsigned _sp = 0; while (cond) { \
;     if ((++_sp & 255u) == 0u) { if (xb_ld(&(bar)[XB_TMO])) break; if (_sp > XB_SPIN_CAP) { atomicAdd(&(bar)[XB_TMO], 1u); break; } } } } while (0)
; __device__ __forceinline__ void xcd_barrier(unsigned* barw, volatile LAS unsigned* stw, const int wv) {
;     ...
;             else XB_SPIN(xb_ld(&bar[XB_TOPGEN]) == tg, bar);
;             __builtin_amdgcn_fence(__ATOMIC_ACQUIRE, "agent");
;             xb_add(&bar[XB_XGEN(b.x)], 1u);
;             asm volatile("s_waitcnt vmcnt(0)" ::: "memory");
.LBB0_356:
	s_or_b64 exec, exec, s[10:11]
	s_mov_b64 s[10:11], exec
	v_mbcnt_lo_u32_b32 v0, s10, 0
	v_mbcnt_hi_u32_b32 v0, s11, v0
	v_cmp_eq_u32_e32 vcc, 0, v0
	s_waitcnt vmcnt(0)
	s_and_saveexec_b64 s[14:15], vcc
	s_cbranch_execz .LBB0_358

; __device__ __forceinline__ unsigned xb_ld(unsigned* p)              { return __hip_atomic_load(p, __ATOMIC_RELAXED, __HIP_MEMORY_SCOPE_AGENT); }
; __device__ __forceinline__ unsigned xb_add(unsigned* p, unsigned v) { return __hip_atomic_fetch_add(p, v, __ATOMIC_RELAXED, __HIP_MEMORY_SCOPE_AGENT); }
; #define XB_SPIN(cond, bar) do { unsigned _sp = 0; while (cond) { \
;     if ((++_sp & 255u) == 0u) { if (xb_ld(&(bar)[XB_TMO])) break; if (_sp > XB_SPIN_CAP) { atomicAdd(&(bar)[XB_TMO], 1u); break; } } } } while (0)
; __device__ __forceinline__ void xcd_barrier(unsigned* barw, volatile LAS unsigned* stw, const int wv) {
;     ...
;         const unsigned old = xb_add(&bar[XB_XSUB(b.x)], 1u);
;         const unsigned gen = old / nloc;
;         if (old + 1u == (gen + 1u) * nloc) {
;             __builtin_amdgcn_fence(__ATOMIC_RELEASE, "agent");
;             asm volatile("s_waitcnt vmcnt(0)" ::: "memory");
;             const unsigned og = xb_add(&bar[XB_TOP], 1u);
;             const unsigned tg = og / nx;
;             if (og + 1u == (tg + 1u) * nx) xb_add(&bar[XB_TOPGEN], 1u);
;             else XB_SPIN(xb_ld(&bar[XB_TOPGEN]) == tg, bar);
;             __builtin_amdgcn_fence(__ATOMIC_ACQUIRE, "agent");
;             xb_add(&bar[XB_XGEN(b.x)], 1u);
;             asm volatile("s_waitcnt vmcnt(0)" ::: "memory");
;         } else {
;             XB_SPIN(xb_ld(&bar[XB_XGEN(b.x)]) == gen, bar);
.LBB0_481:
	s_or_b64 exec, exec, s[18:19]
	v_cvt_f32_u32_e32 v4, v2
	s_waitcnt vmcnt(0)
	v_readfirstlane_b32 s4, v3
	v_sub_u32_e32 v3, 0, v2
	v_rcp_iflag_f32_e32 v4, v4
	v_add_u32_e32 v5, s4, v1
	v_mul_f32_e32 v4, 0x4f7ffffe, v4
	v_cvt_u32_f32_e32 v4, v4
	v_mul_lo_u32 v1, v3, v4
	v_mul_hi_u32 v1, v4, v1
	v_add_u32_e32 v1, v4, v1
	v_mul_hi_u32 v1, v5, v1
	v_mul_lo_u32 v3, v1, v2
	v_sub_u32_e32 v3, v5, v3
	v_add_u32_e32 v4, 1, v1
	v_cmp_ge_u32_e32 vcc, v3, v2
	s_nop 1
	v_cndmask_b32_e32 v1, v1, v4, vcc
	v_sub_u32_e32 v4, v3, v2
	v_cndmask_b32_e32 v3, v3, v4, vcc
	v_add_u32_e32 v4, 1, v1
	v_cmp_ge_u32_e32 vcc, v3, v2
	v_add_u32_e32 v3, 1, v5
	s_nop 0
	v_cndmask_b32_e32 v1, v1, v4, vcc
	v_mul_lo_u32 v4, v2, v1
	v_add_u32_e32 v2, v4, v2
	v_cmp_ne_u32_e32 vcc, v3, v2
	s_and_saveexec_b64 s[4:5], vcc
	s_xor_b64 s[14:15], exec, s[4:5]
	s_cbranch_execz .LBB0_495
	s_waitcnt lgkmcnt(0)
	buffer_inv sc1
	v_mov_b32_e32 v0, 0x3100
	global_load_dword v0, v0, s[16:17] offset:1024 sc1
	s_add_u32 s20, s16, 0x3500
	s_addc_u32 s21, s17, 0
	s_waitcnt vmcnt(0)
	v_cmp_eq_u32_e32 vcc, v0, v1
	s_and_saveexec_b64 s[18:19], vcc
	s_cbranch_execz .LBB0_494
	s_mov_b32 s4, 1
	s_mov_b64 s[22:23], 0
	v_mov_b32_e32 v0, 0
	s_branch .LBB0_485

; __device__ __forceinline__ unsigned xb_ld(unsigned* p)              { return __hip_atomic_load(p, __ATOMIC_RELAXED, __HIP_MEMORY_SCOPE_AGENT); }
; __device__ __forceinline__ unsigned xb_add(unsigned* p, unsigned v) { return __hip_atomic_fetch_add(p, v, __ATOMIC_RELAXED, __HIP_MEMORY_SCOPE_AGENT); }
; #define XB_SPIN(cond, bar) do { unsigned _sp = 0; while (cond) { \
;     if ((++_sp & 255u) == 0u) { if (xb_ld(&(bar)[XB_TMO])) break; if (_sp > XB_SPIN_CAP) { atomicAdd(&(bar)[XB_TMO], 1u); break; } } } } while (0)
; __device__ __forceinline__ void xcd_barrier(unsigned* barw, volatile LAS unsigned* stw, const int wv) {
;     ...
;         if (old + 1u == (gen + 1u) * nloc) {
;             __builtin_amdgcn_fence(__ATOMIC_RELEASE, "agent");
;             asm volatile("s_waitcnt vmcnt(0)" ::: "memory");
;             const unsigned og = xb_add(&bar[XB_TOP], 1u);
;             const unsigned tg = og / nx;
;             if (og + 1u == (tg + 1u) * nx) xb_add(&bar[XB_TOPGEN], 1u);
;             else XB_SPIN(xb_ld(&bar[XB_TOPGEN]) == tg, bar);
.LBB0_495:
	s_andn2_saveexec_b64 s[4:5], s[14:15]
	s_cbranch_execz .LBB0_515
	s_mov_b64 s[14:15], exec
	buffer_wbl2 sc1
	buffer_inv sc1
	s_waitcnt lgkmcnt(0)
	s_waitcnt vmcnt(0)
	v_mbcnt_lo_u32_b32 v1, s14, 0
	v_mbcnt_hi_u32_b32 v1, s15, v1
	v_cmp_eq_u32_e32 vcc, 0, v1
	s_and_saveexec_b64 s[18:19], vcc
	s_cbranch_execz .LBB0_498
	s_bcnt1_i32_b64 s4, s[14:15]
	v_mov_b32_e32 v2, 0x3000
	v_mov_b32_e32 v3, s4
	global_atomic_add v2, v2, v3, s[16:17] offset:1024 sc0

; __device__ __forceinline__ unsigned xb_ld(unsigned* p)              { return __hip_atomic_load(p, __ATOMIC_RELAXED, __HIP_MEMORY_SCOPE_AGENT); }
; __device__ __forceinline__ unsigned xb_add(unsigned* p, unsigned v) { return __hip_atomic_fetch_add(p, v, __ATOMIC_RELAXED, __HIP_MEMORY_SCOPE_AGENT); }
; #define XB_SPIN(cond, bar) do { unsigned _sp = 0; while (cond) { \
;     if ((++_sp & 255u) == 0u) { if (xb_ld(&(bar)[XB_TMO])) break; if (_sp > XB_SPIN_CAP) { atomicAdd(&(bar)[XB_TMO], 1u); break; } } } } while (0)
; __device__ __forceinline__ void xcd_barrier(unsigned* barw, volatile LAS unsigned* stw, const int wv) {
;     ...
;         const unsigned old = xb_add(&bar[XB_XSUB(b.x)], 1u);
;         const unsigned gen = old / nloc;
;         if (old + 1u == (gen + 1u) * nloc) {
;             __builtin_amdgcn_fence(__ATOMIC_RELEASE, "agent");
;             asm volatile("s_waitcnt vmcnt(0)" ::: "memory");
;             const unsigned og = xb_add(&bar[XB_TOP], 1u);
;             const unsigned tg = og / nx;
;             if (og + 1u == (tg + 1u) * nx) xb_add(&bar[XB_TOPGEN], 1u);
;             else XB_SPIN(xb_ld(&bar[XB_TOPGEN]) == tg, bar);
;             __builtin_amdgcn_fence(__ATOMIC_ACQUIRE, "agent");
;             xb_add(&bar[XB_XGEN(b.x)], 1u);
;             asm volatile("s_waitcnt vmcnt(0)" ::: "memory");
;         } else {
;             XB_SPIN(xb_ld(&bar[XB_XGEN(b.x)]) == gen, bar);
.LBB0_740:
	s_lshl_b32 s4, s4, 8
	s_add_u32 s12, s10, s4
	s_addc_u32 s13, s11, 0
	v_mov_b32_e32 v1, 0x1000
	v_mov_b32_e32 v3, 1
	global_atomic_add v3, v1, v3, s[12:13] offset:1024 sc0
	v_cvt_f32_u32_e32 v1, v2
	v_sub_u32_e32 v4, 0, v2
	v_rcp_iflag_f32_e32 v1, v1
	s_nop 0
	v_mul_f32_e32 v1, 0x4f7ffffe, v1
	v_cvt_u32_f32_e32 v1, v1
	v_mul_lo_u32 v4, v4, v1
	v_mul_hi_u32 v4, v1, v4
	v_add_u32_e32 v1, v1, v4
	s_waitcnt vmcnt(0)
	v_mul_hi_u32 v1, v3, v1
	v_mul_lo_u32 v4, v1, v2
	v_sub_u32_e32 v4, v3, v4
	v_add_u32_e32 v5, 1, v1
	v_cmp_ge_u32_e32 vcc, v4, v2
	v_add_u32_e32 v3, 1, v3
	s_nop 0
	v_cndmask_b32_e32 v1, v1, v5, vcc
	v_sub_u32_e32 v5, v4, v2
	v_cndmask_b32_e32 v4, v4, v5, vcc
	v_add_u32_e32 v5, 1, v1
	v_cmp_ge_u32_e32 vcc, v4, v2
	s_nop 1
	v_cndmask_b32_e32 v1, v1, v5, vcc
	v_mul_lo_u32 v4, v2, v1
	v_add_u32_e32 v2, v4, v2
	v_cmp_ne_u32_e32 vcc, v3, v2
	s_and_saveexec_b64 s[4:5], vcc
	s_xor_b64 s[14:15], exec, s[4:5]
	s_cbranch_execz .LBB0_753
	s_waitcnt lgkmcnt(0)
	buffer_inv sc1
	v_mov_b32_e32 v0, 0x3100
	global_load_dword v0, v0, s[10:11] offset:1024 sc1
	s_add_u32 s18, s10, 0x3500
	s_addc_u32 s19, s11, 0
	s_waitcnt vmcnt(0)
	v_cmp_eq_u32_e32 vcc, v0, v1
	s_and_saveexec_b64 s[16:17], vcc
	s_cbranch_execz .LBB0_752
	s_mov_b32 s4, 1
	s_mov_b64 s[20:21], 0
	v_mov_b32_e32 v0, 0
	s_branch .LBB0_744

; __device__ __forceinline__ unsigned xb_ld(unsigned* p)              { return __hip_atomic_load(p, __ATOMIC_RELAXED, __HIP_MEMORY_SCOPE_AGENT); }
; __device__ __forceinline__ unsigned xb_add(unsigned* p, unsigned v) { return __hip_atomic_fetch_add(p, v, __ATOMIC_RELAXED, __HIP_MEMORY_SCOPE_AGENT); }
; #define XB_SPIN(cond, bar) do { unsigned _sp = 0; while (cond) { \
;     if ((++_sp & 255u) == 0u) { if (xb_ld(&(bar)[XB_TMO])) break; if (_sp > XB_SPIN_CAP) { atomicAdd(&(bar)[XB_TMO], 1u); break; } } } } while (0)
; __device__ __forceinline__ void xcd_barrier(unsigned* barw, volatile LAS unsigned* stw, const int wv) {
;     ...
;         if (old + 1u == (gen + 1u) * nloc) {
;             __builtin_amdgcn_fence(__ATOMIC_RELEASE, "agent");
;             asm volatile("s_waitcnt vmcnt(0)" ::: "memory");
;             const unsigned og = xb_add(&bar[XB_TOP], 1u);
;             const unsigned tg = og / nx;
;             if (og + 1u == (tg + 1u) * nx) xb_add(&bar[XB_TOPGEN], 1u);
;             else XB_SPIN(xb_ld(&bar[XB_TOPGEN]) == tg, bar);
;             __builtin_amdgcn_fence(__ATOMIC_ACQUIRE, "agent");
;             xb_add(&bar[XB_XGEN(b.x)], 1u);
;             asm volatile("s_waitcnt vmcnt(0)" ::: "memory");
;         } else {
;             XB_SPIN(xb_ld(&bar[XB_XGEN(b.x)]) == gen, bar);
;             __builtin_amdgcn_fence(__ATOMIC_ACQUIRE, "agent");
;             asm volatile("s_waitcnt vmcnt(0)" ::: "memory");
.LBB0_752:
	s_or_b64 exec, exec, s[16:17]
	s_waitcnt vmcnt(0)
	s_waitcnt vmcnt(0)
.LBB0_753:
	s_andn2_saveexec_b64 s[4:5], s[14:15]
	s_cbranch_execz .LBB0_769
	buffer_wbl2 sc1
	buffer_inv sc1
	s_waitcnt lgkmcnt(0)
	s_waitcnt vmcnt(0)
	v_mov_b32_e32 v1, 0x3000
	v_mov_b32_e32 v2, 1
	global_atomic_add v1, v1, v2, s[10:11] offset:1024 sc0
	v_cvt_f32_u32_e32 v2, v0
	v_sub_u32_e32 v3, 0, v0
	s_add_u32 s10, s10, 0x3500
	s_addc_u32 s11, s11, 0
	v_rcp_iflag_f32_e32 v2, v2
	s_mov_b64 s[16:17], -1
	v_mul_f32_e32 v2, 0x4f7ffffe, v2
	v_cvt_u32_f32_e32 v2, v2
	v_mul_lo_u32 v3, v3, v2
	v_mul_hi_u32 v3, v2, v3
	v_add_u32_e32 v2, v2, v3
	s_waitcnt vmcnt(0)
	v_mul_hi_u32 v2, v1, v2
	v_mul_lo_u32 v4, v2, v0
	v_add_u32_e32 v3, 1, v1
	v_sub_u32_e32 v1, v1, v4
	v_add_u32_e32 v5, 1, v2
	v_cmp_ge_u32_e32 vcc, v1, v0
	v_sub_u32_e32 v4, v1, v0
	s_nop 0
	v_cndmask_b32_e32 v2, v2, v5, vcc
	v_cndmask_b32_e32 v1, v1, v4, vcc
	v_add_u32_e32 v4, 1, v2
	v_cmp_ge_u32_e32 vcc, v1, v0
	s_nop 1
	v_cndmask_b32_e32 v2, v2, v4, vcc
	v_mul_lo_u32 v1, v0, v2
	v_add_u32_e32 v0, v1, v0
	v_cmp_ne_u32_e32 vcc, v3, v0
	v_mov_b64_e32 v[0:1], s[10:11]
	s_and_saveexec_b64 s[14:15], vcc
	s_cbranch_execz .LBB0_766
	v_mov_b32_e32 v0, 0
	global_load_dword v1, v0, s[10:11] sc1
	s_mov_b64 s[18:19], 0
	s_waitcnt vmcnt(0)
	v_cmp_eq_u32_e32 vcc, v1, v2
	s_and_saveexec_b64 s[16:17], vcc
	s_cbranch_execz .LBB0_765
	s_mov_b32 s4, 1
	s_branch .LBB0_758

; __device__ __forceinline__ unsigned xb_ld(unsigned* p)              { return __hip_atomic_load(p, __ATOMIC_RELAXED, __HIP_MEMORY_SCOPE_AGENT); }
; __device__ __forceinline__ unsigned xb_add(unsigned* p, unsigned v) { return __hip_atomic_fetch_add(p, v, __ATOMIC_RELAXED, __HIP_MEMORY_SCOPE_AGENT); }
; #define XB_SPIN(cond, bar) do { unsigned _sp = 0; while (cond) { \
;     if ((++_sp & 255u) == 0u) { if (xb_ld(&(bar)[XB_TMO])) break; if (_sp > XB_SPIN_CAP) { atomicAdd(&(bar)[XB_TMO], 1u); break; } } } } while (0)
; __device__ __forceinline__ void xcd_barrier(unsigned* barw, volatile LAS unsigned* stw, const int wv) {
;     ...
;             else XB_SPIN(xb_ld(&bar[XB_TOPGEN]) == tg, bar);
;             __builtin_amdgcn_fence(__ATOMIC_ACQUIRE, "agent");
;             xb_add(&bar[XB_XGEN(b.x)], 1u);
;             asm volatile("s_waitcnt vmcnt(0)" ::: "memory");
.LBB0_768:
	s_or_b64 exec, exec, s[8:9]
	s_waitcnt vmcnt(0)
	s_waitcnt vmcnt(0)

; __device__ __forceinline__ unsigned xb_ld(unsigned* p)              { return __hip_atomic_load(p, __ATOMIC_RELAXED, __HIP_MEMORY_SCOPE_AGENT); }
; __device__ __forceinline__ unsigned xb_add(unsigned* p, unsigned v) { return __hip_atomic_fetch_add(p, v, __ATOMIC_RELAXED, __HIP_MEMORY_SCOPE_AGENT); }
; #define XB_SPIN(cond, bar) do { unsigned _sp = 0; while (cond) { \
;     if ((++_sp & 255u) == 0u) { if (xb_ld(&(bar)[XB_TMO])) break; if (_sp > XB_SPIN_CAP) { atomicAdd(&(bar)[XB_TMO], 1u); break; } } } } while (0)
; __device__ __forceinline__ void xcd_barrier(unsigned* barw, volatile LAS unsigned* stw, const int wv) {
;     ...
;         const unsigned old = xb_add(&bar[XB_XSUB(b.x)], 1u);
;         const unsigned gen = old / nloc;
;         if (old + 1u == (gen + 1u) * nloc) {
;             __builtin_amdgcn_fence(__ATOMIC_RELEASE, "agent");
;             asm volatile("s_waitcnt vmcnt(0)" ::: "memory");
;             const unsigned og = xb_add(&bar[XB_TOP], 1u);
;             const unsigned tg = og / nx;
;             if (og + 1u == (tg + 1u) * nx) xb_add(&bar[XB_TOPGEN], 1u);
;             else XB_SPIN(xb_ld(&bar[XB_TOPGEN]) == tg, bar);
;             __builtin_amdgcn_fence(__ATOMIC_ACQUIRE, "agent");
;             xb_add(&bar[XB_XGEN(b.x)], 1u);
;             asm volatile("s_waitcnt vmcnt(0)" ::: "memory");
;         } else {
;             XB_SPIN(xb_ld(&bar[XB_XGEN(b.x)]) == gen, bar);
.LBB0_800:
	s_lshl_b32 s0, s4, 8
	s_mov_b32 s1, 0
	v_lshl_add_u64 v[4:5], v[2:3], 0, s[0:1]
	v_add_co_u32_e32 v10, vcc, 0x1000, v4
	v_mov_b32_e32 v7, 1
	s_nop 0
	v_addc_co_u32_e32 v11, vcc, 0, v5, vcc
	global_atomic_add v7, v[10:11], v7, off offset:1024 sc0
	v_cvt_f32_u32_e32 v9, v8
	v_sub_u32_e32 v10, 0, v8
	v_rcp_iflag_f32_e32 v9, v9
	s_nop 0
	v_mul_f32_e32 v9, 0x4f7ffffe, v9
	v_cvt_u32_f32_e32 v9, v9
	v_mul_lo_u32 v10, v10, v9
	v_mul_hi_u32 v10, v9, v10
	v_add_u32_e32 v9, v9, v10
	s_waitcnt vmcnt(0)
	v_mul_hi_u32 v9, v7, v9
	v_mul_lo_u32 v11, v9, v8
	v_add_u32_e32 v10, 1, v7
	v_sub_u32_e32 v7, v7, v11
	v_add_u32_e32 v12, 1, v9
	v_cmp_ge_u32_e32 vcc, v7, v8
	v_sub_u32_e32 v11, v7, v8
	s_nop 0
	v_cndmask_b32_e32 v9, v9, v12, vcc
	v_cndmask_b32_e32 v7, v7, v11, vcc
	v_add_u32_e32 v11, 1, v9
	v_cmp_ge_u32_e32 vcc, v7, v8
	s_nop 1
	v_cndmask_b32_e32 v7, v9, v11, vcc
	v_mad_u64_u32 v[8:9], s[0:1], v8, v7, v[8:9]
	v_cmp_ne_u32_e32 vcc, v10, v8
	s_and_saveexec_b64 s[0:1], vcc
	s_xor_b64 s[0:1], exec, s[0:1]
	s_cbranch_execz .LBB0_813
	buffer_inv sc1
	v_add_co_u32_e32 v2, vcc, 0x3500, v2
	s_nop 1
	v_addc_co_u32_e32 v3, vcc, 0, v3, vcc
	global_load_dword v4, v[2:3], off sc1
	s_waitcnt vmcnt(0)
	v_cmp_eq_u32_e32 vcc, v4, v7
	s_and_saveexec_b64 s[8:9], vcc
	s_cbranch_execz .LBB0_812
	s_mov_b32 s4, 1
	s_mov_b64 s[10:11], 0
	s_branch .LBB0_804

; __device__ __forceinline__ unsigned xb_ld(unsigned* p)              { return __hip_atomic_load(p, __ATOMIC_RELAXED, __HIP_MEMORY_SCOPE_AGENT); }
; __device__ __forceinline__ unsigned xb_add(unsigned* p, unsigned v) { return __hip_atomic_fetch_add(p, v, __ATOMIC_RELAXED, __HIP_MEMORY_SCOPE_AGENT); }
; #define XB_SPIN(cond, bar) do { unsigned _sp = 0; while (cond) { \
;     if ((++_sp & 255u) == 0u) { if (xb_ld(&(bar)[XB_TMO])) break; if (_sp > XB_SPIN_CAP) { atomicAdd(&(bar)[XB_TMO], 1u); break; } } } } while (0)
; __device__ __forceinline__ void xcd_barrier(unsigned* barw, volatile LAS unsigned* stw, const int wv) {
;     ...
;         if (old + 1u == (gen + 1u) * nloc) {
;             __builtin_amdgcn_fence(__ATOMIC_RELEASE, "agent");
;             asm volatile("s_waitcnt vmcnt(0)" ::: "memory");
;             const unsigned og = xb_add(&bar[XB_TOP], 1u);
;             const unsigned tg = og / nx;
;             if (og + 1u == (tg + 1u) * nx) xb_add(&bar[XB_TOPGEN], 1u);
;             else XB_SPIN(xb_ld(&bar[XB_TOPGEN]) == tg, bar);
;             __builtin_amdgcn_fence(__ATOMIC_ACQUIRE, "agent");
;             xb_add(&bar[XB_XGEN(b.x)], 1u);
;             asm volatile("s_waitcnt vmcnt(0)" ::: "memory");
;         } else {
;             XB_SPIN(xb_ld(&bar[XB_XGEN(b.x)]) == gen, bar);
;             __builtin_amdgcn_fence(__ATOMIC_ACQUIRE, "agent");
;             asm volatile("s_waitcnt vmcnt(0)" ::: "memory");
.LBB0_812:
	s_or_b64 exec, exec, s[8:9]
	s_waitcnt vmcnt(0) lgkmcnt(0)
	s_waitcnt vmcnt(0)
.LBB0_813:
	s_andn2_saveexec_b64 s[0:1], s[0:1]
	s_cbranch_execz .LBB0_829
	v_add_co_u32_e32 v8, vcc, 0x3000, v2
	buffer_wbl2 sc1
	buffer_inv sc1
	s_waitcnt lgkmcnt(0)
	s_waitcnt vmcnt(0)
	v_addc_co_u32_e32 v9, vcc, 0, v3, vcc
	v_mov_b32_e32 v7, 1
	global_atomic_add v7, v[8:9], v7, off offset:1024 sc0
	v_cvt_f32_u32_e32 v8, v6
	v_sub_u32_e32 v9, 0, v6
	s_mov_b64 s[0:1], 0x3500
	v_lshl_add_u64 v[2:3], v[2:3], 0, s[0:1]
	v_rcp_iflag_f32_e32 v8, v8
	s_mov_b64 s[8:9], -1
	v_mul_f32_e32 v8, 0x4f7ffffe, v8
	v_cvt_u32_f32_e32 v8, v8
	v_mul_lo_u32 v9, v9, v8
	v_mul_hi_u32 v9, v8, v9
	v_add_u32_e32 v8, v8, v9
	s_waitcnt vmcnt(0)
	v_mul_hi_u32 v8, v7, v8
	v_mul_lo_u32 v9, v8, v6
	v_add_u32_e32 v10, 1, v7
	v_sub_u32_e32 v7, v7, v9
	v_add_u32_e32 v11, 1, v8
	v_cmp_ge_u32_e32 vcc, v7, v6
	v_sub_u32_e32 v9, v7, v6
	s_nop 0
	v_cndmask_b32_e32 v8, v8, v11, vcc
	v_cndmask_b32_e32 v7, v7, v9, vcc
	v_add_u32_e32 v9, 1, v8
	v_cmp_ge_u32_e32 vcc, v7, v6
	s_nop 1
	v_cndmask_b32_e32 v7, v8, v9, vcc
	v_mad_u64_u32 v[8:9], s[0:1], v6, v7, v[6:7]
	v_cmp_ne_u32_e32 vcc, v10, v8
	s_and_saveexec_b64 s[0:1], vcc
	s_cbranch_execz .LBB0_826
	global_load_dword v6, v[2:3], off sc1
	s_mov_b64 s[10:11], 0
	s_waitcnt vmcnt(0)
	v_cmp_eq_u32_e32 vcc, v6, v7
	s_and_saveexec_b64 s[8:9], vcc
	s_cbranch_execz .LBB0_825
	s_mov_b32 s4, 1
	s_branch .LBB0_818

; __device__ __forceinline__ unsigned xb_ld(unsigned* p)              { return __hip_atomic_load(p, __ATOMIC_RELAXED, __HIP_MEMORY_SCOPE_AGENT); }
; __device__ __forceinline__ unsigned xb_add(unsigned* p, unsigned v) { return __hip_atomic_fetch_add(p, v, __ATOMIC_RELAXED, __HIP_MEMORY_SCOPE_AGENT); }
; #define XB_SPIN(cond, bar) do { unsigned _sp = 0; while (cond) { \
;     if ((++_sp & 255u) == 0u) { if (xb_ld(&(bar)[XB_TMO])) break; if (_sp > XB_SPIN_CAP) { atomicAdd(&(bar)[XB_TMO], 1u); break; } } } } while (0)
; __device__ __forceinline__ void xcd_barrier(unsigned* barw, volatile LAS unsigned* stw, const int wv) {
;     ...
;             else XB_SPIN(xb_ld(&bar[XB_TOPGEN]) == tg, bar);
;             __builtin_amdgcn_fence(__ATOMIC_ACQUIRE, "agent");
;             xb_add(&bar[XB_XGEN(b.x)], 1u);
;             asm volatile("s_waitcnt vmcnt(0)" ::: "memory");
.LBB0_828:
	s_or_b64 exec, exec, s[0:1]
	s_waitcnt vmcnt(0)
	s_waitcnt vmcnt(0)

; __device__ __forceinline__ unsigned xb_ld(unsigned* p)              { return __hip_atomic_load(p, __ATOMIC_RELAXED, __HIP_MEMORY_SCOPE_AGENT); }
; __device__ __forceinline__ unsigned xb_add(unsigned* p, unsigned v) { return __hip_atomic_fetch_add(p, v, __ATOMIC_RELAXED, __HIP_MEMORY_SCOPE_AGENT); }
; #define XB_SPIN(cond, bar) do { unsigned _sp = 0; while (cond) { \
;     if ((++_sp & 255u) == 0u) { if (xb_ld(&(bar)[XB_TMO])) break; if (_sp > XB_SPIN_CAP) { atomicAdd(&(bar)[XB_TMO], 1u); break; } } } } while (0)
; __device__ __forceinline__ void xcd_barrier(unsigned* barw, volatile LAS unsigned* stw, const int wv) {
;     ...
;         const unsigned old = xb_add(&bar[XB_XSUB(b.x)], 1u);
;         const unsigned gen = old / nloc;
;         if (old + 1u == (gen + 1u) * nloc) {
;             __builtin_amdgcn_fence(__ATOMIC_RELEASE, "agent");
;             asm volatile("s_waitcnt vmcnt(0)" ::: "memory");
;             const unsigned og = xb_add(&bar[XB_TOP], 1u);
;             const unsigned tg = og / nx;
;             if (og + 1u == (tg + 1u) * nx) xb_add(&bar[XB_TOPGEN], 1u);
;             else XB_SPIN(xb_ld(&bar[XB_TOPGEN]) == tg, bar);
;             __builtin_amdgcn_fence(__ATOMIC_ACQUIRE, "agent");
;             xb_add(&bar[XB_XGEN(b.x)], 1u);
;             asm volatile("s_waitcnt vmcnt(0)" ::: "memory");
;         } else {
;             XB_SPIN(xb_ld(&bar[XB_XGEN(b.x)]) == gen, bar);
.LBB0_865:
	s_or_b64 exec, exec, s[16:17]
	v_cvt_f32_u32_e32 v4, v2
	s_waitcnt vmcnt(0)
	v_readfirstlane_b32 s4, v3
	v_sub_u32_e32 v3, 0, v2
	v_rcp_iflag_f32_e32 v4, v4
	v_add_u32_e32 v5, s4, v1
	v_mul_f32_e32 v4, 0x4f7ffffe, v4
	v_cvt_u32_f32_e32 v4, v4
	v_mul_lo_u32 v1, v3, v4
	v_mul_hi_u32 v1, v4, v1
	v_add_u32_e32 v1, v4, v1
	v_mul_hi_u32 v1, v5, v1
	v_mul_lo_u32 v3, v1, v2
	v_sub_u32_e32 v3, v5, v3
	v_add_u32_e32 v4, 1, v1
	v_cmp_ge_u32_e32 vcc, v3, v2
	s_nop 1
	v_cndmask_b32_e32 v1, v1, v4, vcc
	v_sub_u32_e32 v4, v3, v2
	v_cndmask_b32_e32 v3, v3, v4, vcc
	v_add_u32_e32 v4, 1, v1
	v_cmp_ge_u32_e32 vcc, v3, v2
	v_add_u32_e32 v3, 1, v5
	s_nop 0
	v_cndmask_b32_e32 v1, v1, v4, vcc
	v_mul_lo_u32 v4, v2, v1
	v_add_u32_e32 v2, v4, v2
	v_cmp_ne_u32_e32 vcc, v3, v2
	s_and_saveexec_b64 s[4:5], vcc
	s_xor_b64 s[14:15], exec, s[4:5]
	s_cbranch_execz .LBB0_879
	s_waitcnt lgkmcnt(0)
	buffer_inv sc1
	v_mov_b32_e32 v0, 0x3100
	global_load_dword v0, v0, s[12:13] offset:1024 sc1
	s_add_u32 s18, s12, 0x3500
	s_addc_u32 s19, s13, 0
	s_waitcnt vmcnt(0)
	v_cmp_eq_u32_e32 vcc, v0, v1
	s_and_saveexec_b64 s[16:17], vcc
	s_cbranch_execz .LBB0_878
	s_mov_b32 s4, 1
	s_mov_b64 s[20:21], 0
	v_mov_b32_e32 v0, 0
	s_branch .LBB0_869

; __device__ __forceinline__ unsigned xb_ld(unsigned* p)              { return __hip_atomic_load(p, __ATOMIC_RELAXED, __HIP_MEMORY_SCOPE_AGENT); }
; __device__ __forceinline__ unsigned xb_add(unsigned* p, unsigned v) { return __hip_atomic_fetch_add(p, v, __ATOMIC_RELAXED, __HIP_MEMORY_SCOPE_AGENT); }
; #define XB_SPIN(cond, bar) do { unsigned _sp = 0; while (cond) { \
;     if ((++_sp & 255u) == 0u) { if (xb_ld(&(bar)[XB_TMO])) break; if (_sp > XB_SPIN_CAP) { atomicAdd(&(bar)[XB_TMO], 1u); break; } } } } while (0)
; __device__ __forceinline__ void xcd_barrier(unsigned* barw, volatile LAS unsigned* stw, const int wv) {
;     ...
;         if (old + 1u == (gen + 1u) * nloc) {
;             __builtin_amdgcn_fence(__ATOMIC_RELEASE, "agent");
;             asm volatile("s_waitcnt vmcnt(0)" ::: "memory");
;             const unsigned og = xb_add(&bar[XB_TOP], 1u);
;             const unsigned tg = og / nx;
;             if (og + 1u == (tg + 1u) * nx) xb_add(&bar[XB_TOPGEN], 1u);
;             else XB_SPIN(xb_ld(&bar[XB_TOPGEN]) == tg, bar);
.LBB0_879:
	s_andn2_saveexec_b64 s[4:5], s[14:15]
	s_cbranch_execz .LBB0_899
	s_mov_b64 s[14:15], exec
	buffer_wbl2 sc1
	buffer_inv sc1
	s_waitcnt lgkmcnt(0)
	s_waitcnt vmcnt(0)
	v_mbcnt_lo_u32_b32 v1, s14, 0
	v_mbcnt_hi_u32_b32 v1, s15, v1
	v_cmp_eq_u32_e32 vcc, 0, v1
	s_and_saveexec_b64 s[16:17], vcc
	s_cbranch_execz .LBB0_882
	s_bcnt1_i32_b64 s4, s[14:15]
	v_mov_b32_e32 v2, 0x3000
	v_mov_b32_e32 v3, s4
	global_atomic_add v2, v2, v3, s[12:13] offset:1024 sc0

; __device__ __forceinline__ unsigned xb_ld(unsigned* p)              { return __hip_atomic_load(p, __ATOMIC_RELAXED, __HIP_MEMORY_SCOPE_AGENT); }
; __device__ __forceinline__ unsigned xb_add(unsigned* p, unsigned v) { return __hip_atomic_fetch_add(p, v, __ATOMIC_RELAXED, __HIP_MEMORY_SCOPE_AGENT); }
; #define XB_SPIN(cond, bar) do { unsigned _sp = 0; while (cond) { \
;     if ((++_sp & 255u) == 0u) { if (xb_ld(&(bar)[XB_TMO])) break; if (_sp > XB_SPIN_CAP) { atomicAdd(&(bar)[XB_TMO], 1u); break; } } } } while (0)
; __device__ __forceinline__ void xcd_barrier(unsigned* barw, volatile LAS unsigned* stw, const int wv) {
;     ...
;             else XB_SPIN(xb_ld(&bar[XB_TOPGEN]) == tg, bar);
;             __builtin_amdgcn_fence(__ATOMIC_ACQUIRE, "agent");
;             xb_add(&bar[XB_XGEN(b.x)], 1u);
;             asm volatile("s_waitcnt vmcnt(0)" ::: "memory");
.LBB0_896:
	s_or_b64 exec, exec, s[8:9]
	s_mov_b64 s[8:9], exec
	v_mbcnt_lo_u32_b32 v0, s8, 0
	v_mbcnt_hi_u32_b32 v0, s9, v0
	v_cmp_eq_u32_e32 vcc, 0, v0
	s_waitcnt vmcnt(0)
	s_and_saveexec_b64 s[12:13], vcc
	s_cbranch_execz .LBB0_898

; __device__ __forceinline__ unsigned xb_ld(unsigned* p)              { return __hip_atomic_load(p, __ATOMIC_RELAXED, __HIP_MEMORY_SCOPE_AGENT); }
; __device__ __forceinline__ unsigned xb_add(unsigned* p, unsigned v) { return __hip_atomic_fetch_add(p, v, __ATOMIC_RELAXED, __HIP_MEMORY_SCOPE_AGENT); }
; #define XB_SPIN(cond, bar) do { unsigned _sp = 0; while (cond) { \
;     if ((++_sp & 255u) == 0u) { if (xb_ld(&(bar)[XB_TMO])) break; if (_sp > XB_SPIN_CAP) { atomicAdd(&(bar)[XB_TMO], 1u); break; } } } } while (0)
; __device__ __forceinline__ void xcd_barrier(unsigned* barw, volatile LAS unsigned* stw, const int wv) {
;     ...
;         const unsigned old = xb_add(&bar[XB_XSUB(b.x)], 1u);
;         const unsigned gen = old / nloc;
;         if (old + 1u == (gen + 1u) * nloc) {
;             __builtin_amdgcn_fence(__ATOMIC_RELEASE, "agent");
;             asm volatile("s_waitcnt vmcnt(0)" ::: "memory");
;             const unsigned og = xb_add(&bar[XB_TOP], 1u);
;             const unsigned tg = og / nx;
;             if (og + 1u == (tg + 1u) * nx) xb_add(&bar[XB_TOPGEN], 1u);
;             else XB_SPIN(xb_ld(&bar[XB_TOPGEN]) == tg, bar);
;             __builtin_amdgcn_fence(__ATOMIC_ACQUIRE, "agent");
;             xb_add(&bar[XB_XGEN(b.x)], 1u);
;             asm volatile("s_waitcnt vmcnt(0)" ::: "memory");
;         } else {
;             XB_SPIN(xb_ld(&bar[XB_XGEN(b.x)]) == gen, bar);
.LBB0_959:
	s_or_b64 exec, exec, s[10:11]
	v_cvt_f32_u32_e32 v4, v2
	s_waitcnt vmcnt(0)
	v_readfirstlane_b32 s8, v3
	v_sub_u32_e32 v3, 0, v2
	v_rcp_iflag_f32_e32 v4, v4
	v_add_u32_e32 v5, s8, v1
	v_mul_f32_e32 v4, 0x4f7ffffe, v4
	v_cvt_u32_f32_e32 v4, v4
	v_mul_lo_u32 v1, v3, v4
	v_mul_hi_u32 v1, v4, v1
	v_add_u32_e32 v1, v4, v1
	v_mul_hi_u32 v1, v5, v1
	v_mul_lo_u32 v3, v1, v2
	v_sub_u32_e32 v3, v5, v3
	v_add_u32_e32 v4, 1, v1
	v_cmp_ge_u32_e32 vcc, v3, v2
	s_nop 1
	v_cndmask_b32_e32 v1, v1, v4, vcc
	v_sub_u32_e32 v4, v3, v2
	v_cndmask_b32_e32 v3, v3, v4, vcc
	v_add_u32_e32 v4, 1, v1
	v_cmp_ge_u32_e32 vcc, v3, v2
	v_add_u32_e32 v3, 1, v5
	s_nop 0
	v_cndmask_b32_e32 v1, v1, v4, vcc
	v_mul_lo_u32 v4, v2, v1
	v_add_u32_e32 v2, v4, v2
	v_cmp_ne_u32_e32 vcc, v3, v2
	s_and_saveexec_b64 s[8:9], vcc
	s_xor_b64 s[8:9], exec, s[8:9]
	s_cbranch_execz .LBB0_973
	s_waitcnt lgkmcnt(0)
	buffer_inv sc1
	v_mov_b32_e32 v0, 0x3100
	global_load_dword v0, v0, s[12:13] offset:1024 sc1
	s_add_u32 s14, s12, 0x3500
	s_addc_u32 s15, s13, 0
	s_waitcnt vmcnt(0)
	v_cmp_eq_u32_e32 vcc, v0, v1
	s_and_saveexec_b64 s[10:11], vcc
	s_cbranch_execz .LBB0_972
	s_mov_b32 s26, 1
	s_mov_b64 s[16:17], 0
	v_mov_b32_e32 v0, 0
	s_branch .LBB0_963

; __device__ __forceinline__ unsigned xb_ld(unsigned* p)              { return __hip_atomic_load(p, __ATOMIC_RELAXED, __HIP_MEMORY_SCOPE_AGENT); }
; __device__ __forceinline__ unsigned xb_add(unsigned* p, unsigned v) { return __hip_atomic_fetch_add(p, v, __ATOMIC_RELAXED, __HIP_MEMORY_SCOPE_AGENT); }
; #define XB_SPIN(cond, bar) do { unsigned _sp = 0; while (cond) { \
;     if ((++_sp & 255u) == 0u) { if (xb_ld(&(bar)[XB_TMO])) break; if (_sp > XB_SPIN_CAP) { atomicAdd(&(bar)[XB_TMO], 1u); break; } } } } while (0)
; __device__ __forceinline__ void xcd_barrier(unsigned* barw, volatile LAS unsigned* stw, const int wv) {
;     ...
;         if (old + 1u == (gen + 1u) * nloc) {
;             __builtin_amdgcn_fence(__ATOMIC_RELEASE, "agent");
;             asm volatile("s_waitcnt vmcnt(0)" ::: "memory");
;             const unsigned og = xb_add(&bar[XB_TOP], 1u);
;             const unsigned tg = og / nx;
;             if (og + 1u == (tg + 1u) * nx) xb_add(&bar[XB_TOPGEN], 1u);
;             else XB_SPIN(xb_ld(&bar[XB_TOPGEN]) == tg, bar);
;             __builtin_amdgcn_fence(__ATOMIC_ACQUIRE, "agent");
;             xb_add(&bar[XB_XGEN(b.x)], 1u);
;             asm volatile("s_waitcnt vmcnt(0)" ::: "memory");
;         } else {
;             XB_SPIN(xb_ld(&bar[XB_XGEN(b.x)]) == gen, bar);
;             __builtin_amdgcn_fence(__ATOMIC_ACQUIRE, "agent");
;             asm volatile("s_waitcnt vmcnt(0)" ::: "memory");
.LBB0_972:
	s_or_b64 exec, exec, s[10:11]
	s_waitcnt vmcnt(0)
	s_waitcnt vmcnt(0)
.LBB0_973:
	s_andn2_saveexec_b64 s[8:9], s[8:9]
	s_cbranch_execz .LBB0_993
	s_mov_b64 s[8:9], exec
	buffer_wbl2 sc1
	buffer_inv sc1
	s_waitcnt lgkmcnt(0)
	s_waitcnt vmcnt(0)
	v_mbcnt_lo_u32_b32 v1, s8, 0
	v_mbcnt_hi_u32_b32 v1, s9, v1
	v_cmp_eq_u32_e32 vcc, 0, v1
	s_and_saveexec_b64 s[10:11], vcc
	s_cbranch_execz .LBB0_976
	s_bcnt1_i32_b64 s8, s[8:9]
	v_mov_b32_e32 v2, 0x3000
	v_mov_b32_e32 v3, s8
	global_atomic_add v2, v2, v3, s[12:13] offset:1024 sc0

; __device__ __forceinline__ unsigned xb_ld(unsigned* p)              { return __hip_atomic_load(p, __ATOMIC_RELAXED, __HIP_MEMORY_SCOPE_AGENT); }
; __device__ __forceinline__ unsigned xb_add(unsigned* p, unsigned v) { return __hip_atomic_fetch_add(p, v, __ATOMIC_RELAXED, __HIP_MEMORY_SCOPE_AGENT); }
; #define XB_SPIN(cond, bar) do { unsigned _sp = 0; while (cond) { \
;     if ((++_sp & 255u) == 0u) { if (xb_ld(&(bar)[XB_TMO])) break; if (_sp > XB_SPIN_CAP) { atomicAdd(&(bar)[XB_TMO], 1u); break; } } } } while (0)
; __device__ __forceinline__ void xcd_barrier(unsigned* barw, volatile LAS unsigned* stw, const int wv) {
;     ...
;             else XB_SPIN(xb_ld(&bar[XB_TOPGEN]) == tg, bar);
;             __builtin_amdgcn_fence(__ATOMIC_ACQUIRE, "agent");
;             xb_add(&bar[XB_XGEN(b.x)], 1u);
;             asm volatile("s_waitcnt vmcnt(0)" ::: "memory");
.LBB0_990:
	s_or_b64 exec, exec, s[4:5]
	s_mov_b64 s[4:5], exec
	v_mbcnt_lo_u32_b32 v0, s4, 0
	v_mbcnt_hi_u32_b32 v0, s5, v0
	v_cmp_eq_u32_e32 vcc, 0, v0
	s_waitcnt vmcnt(0)
	s_and_saveexec_b64 s[8:9], vcc
	s_cbranch_execz .LBB0_992

; __device__ __forceinline__ unsigned xb_ld(unsigned* p)              { return __hip_atomic_load(p, __ATOMIC_RELAXED, __HIP_MEMORY_SCOPE_AGENT); }
; __device__ __forceinline__ unsigned xb_add(unsigned* p, unsigned v) { return __hip_atomic_fetch_add(p, v, __ATOMIC_RELAXED, __HIP_MEMORY_SCOPE_AGENT); }
; #define XB_SPIN(cond, bar) do { unsigned _sp = 0; while (cond) { \
;     if ((++_sp & 255u) == 0u) { if (xb_ld(&(bar)[XB_TMO])) break; if (_sp > XB_SPIN_CAP) { atomicAdd(&(bar)[XB_TMO], 1u); break; } } } } while (0)
; __device__ __forceinline__ void xcd_barrier(unsigned* barw, volatile LAS unsigned* stw, const int wv) {
;     ...
;         const unsigned old = xb_add(&bar[XB_XSUB(b.x)], 1u);
;         const unsigned gen = old / nloc;
;         if (old + 1u == (gen + 1u) * nloc) {
;             __builtin_amdgcn_fence(__ATOMIC_RELEASE, "agent");
;             asm volatile("s_waitcnt vmcnt(0)" ::: "memory");
;             const unsigned og = xb_add(&bar[XB_TOP], 1u);
;             const unsigned tg = og / nx;
;             if (og + 1u == (tg + 1u) * nx) xb_add(&bar[XB_TOPGEN], 1u);
;             else XB_SPIN(xb_ld(&bar[XB_TOPGEN]) == tg, bar);
;             __builtin_amdgcn_fence(__ATOMIC_ACQUIRE, "agent");
;             xb_add(&bar[XB_XGEN(b.x)], 1u);
;             asm volatile("s_waitcnt vmcnt(0)" ::: "memory");
;         } else {
;             XB_SPIN(xb_ld(&bar[XB_XGEN(b.x)]) == gen, bar);
.LBB0_1031:
	s_or_b64 exec, exec, s[10:11]
	v_cvt_f32_u32_e32 v4, v2
	s_waitcnt vmcnt(0)
	v_readfirstlane_b32 s6, v3
	v_sub_u32_e32 v3, 0, v2
	v_rcp_iflag_f32_e32 v4, v4
	v_add_u32_e32 v5, s6, v1
	v_mul_f32_e32 v4, 0x4f7ffffe, v4
	v_cvt_u32_f32_e32 v4, v4
	v_mul_lo_u32 v1, v3, v4
	v_mul_hi_u32 v1, v4, v1
	v_add_u32_e32 v1, v4, v1
	v_mul_hi_u32 v1, v5, v1
	v_mul_lo_u32 v3, v1, v2
	v_sub_u32_e32 v3, v5, v3
	v_add_u32_e32 v4, 1, v1
	v_cmp_ge_u32_e32 vcc, v3, v2
	s_nop 1
	v_cndmask_b32_e32 v1, v1, v4, vcc
	v_sub_u32_e32 v4, v3, v2
	v_cndmask_b32_e32 v3, v3, v4, vcc
	v_add_u32_e32 v4, 1, v1
	v_cmp_ge_u32_e32 vcc, v3, v2
	v_add_u32_e32 v3, 1, v5
	s_nop 0
	v_cndmask_b32_e32 v1, v1, v4, vcc
	v_mul_lo_u32 v4, v2, v1
	v_add_u32_e32 v2, v4, v2
	v_cmp_ne_u32_e32 vcc, v3, v2
	s_and_saveexec_b64 s[6:7], vcc
	s_xor_b64 s[6:7], exec, s[6:7]
	s_cbranch_execz .LBB0_1045
	s_waitcnt lgkmcnt(0)
	buffer_inv sc1
	v_mov_b32_e32 v0, 0x3100
	global_load_dword v0, v0, s[8:9] offset:1024 sc1
	s_add_u32 s12, s8, 0x3500
	s_addc_u32 s13, s9, 0
	s_waitcnt vmcnt(0)
	v_cmp_eq_u32_e32 vcc, v0, v1
	s_and_saveexec_b64 s[10:11], vcc
	s_cbranch_execz .LBB0_1044
	s_mov_b32 s24, 1
	s_mov_b64 s[14:15], 0
	v_mov_b32_e32 v0, 0
	s_branch .LBB0_1035

; __device__ __forceinline__ unsigned xb_ld(unsigned* p)              { return __hip_atomic_load(p, __ATOMIC_RELAXED, __HIP_MEMORY_SCOPE_AGENT); }
; __device__ __forceinline__ unsigned xb_add(unsigned* p, unsigned v) { return __hip_atomic_fetch_add(p, v, __ATOMIC_RELAXED, __HIP_MEMORY_SCOPE_AGENT); }
; #define XB_SPIN(cond, bar) do { unsigned _sp = 0; while (cond) { \
;     if ((++_sp & 255u) == 0u) { if (xb_ld(&(bar)[XB_TMO])) break; if (_sp > XB_SPIN_CAP) { atomicAdd(&(bar)[XB_TMO], 1u); break; } } } } while (0)
; __device__ __forceinline__ void xcd_barrier(unsigned* barw, volatile LAS unsigned* stw, const int wv) {
;     ...
;         if (old + 1u == (gen + 1u) * nloc) {
;             __builtin_amdgcn_fence(__ATOMIC_RELEASE, "agent");
;             asm volatile("s_waitcnt vmcnt(0)" ::: "memory");
;             const unsigned og = xb_add(&bar[XB_TOP], 1u);
;             const unsigned tg = og / nx;
;             if (og + 1u == (tg + 1u) * nx) xb_add(&bar[XB_TOPGEN], 1u);
;             else XB_SPIN(xb_ld(&bar[XB_TOPGEN]) == tg, bar);
.LBB0_1045:
	s_andn2_saveexec_b64 s[6:7], s[6:7]
	s_cbranch_execz .LBB0_1065
	s_mov_b64 s[6:7], exec
	buffer_wbl2 sc1
	buffer_inv sc1
	s_waitcnt lgkmcnt(0)
	s_waitcnt vmcnt(0)
	v_mbcnt_lo_u32_b32 v1, s6, 0
	v_mbcnt_hi_u32_b32 v1, s7, v1
	v_cmp_eq_u32_e32 vcc, 0, v1
	s_and_saveexec_b64 s[10:11], vcc
	s_cbranch_execz .LBB0_1048
	s_bcnt1_i32_b64 s6, s[6:7]
	v_mov_b32_e32 v2, 0x3000
	v_mov_b32_e32 v3, s6
	global_atomic_add v2, v2, v3, s[8:9] offset:1024 sc0

; __device__ __forceinline__ unsigned xb_ld(unsigned* p)              { return __hip_atomic_load(p, __ATOMIC_RELAXED, __HIP_MEMORY_SCOPE_AGENT); }
; __device__ __forceinline__ unsigned xb_add(unsigned* p, unsigned v) { return __hip_atomic_fetch_add(p, v, __ATOMIC_RELAXED, __HIP_MEMORY_SCOPE_AGENT); }
; #define XB_SPIN(cond, bar) do { unsigned _sp = 0; while (cond) { \
;     if ((++_sp & 255u) == 0u) { if (xb_ld(&(bar)[XB_TMO])) break; if (_sp > XB_SPIN_CAP) { atomicAdd(&(bar)[XB_TMO], 1u); break; } } } } while (0)
; __device__ __forceinline__ void xcd_barrier(unsigned* barw, volatile LAS unsigned* stw, const int wv) {
;     ...
;             else XB_SPIN(xb_ld(&bar[XB_TOPGEN]) == tg, bar);
;             __builtin_amdgcn_fence(__ATOMIC_ACQUIRE, "agent");
;             xb_add(&bar[XB_XGEN(b.x)], 1u);
;             asm volatile("s_waitcnt vmcnt(0)" ::: "memory");
.LBB0_1062:
	s_or_b64 exec, exec, s[2:3]
	s_mov_b64 s[2:3], exec
	v_mbcnt_lo_u32_b32 v0, s2, 0
	v_mbcnt_hi_u32_b32 v0, s3, v0
	v_cmp_eq_u32_e32 vcc, 0, v0
	s_waitcnt vmcnt(0)
	s_and_saveexec_b64 s[6:7], vcc
	s_cbranch_execz .LBB0_1064

; __device__ __forceinline__ unsigned xb_ld(unsigned* p)              { return __hip_atomic_load(p, __ATOMIC_RELAXED, __HIP_MEMORY_SCOPE_AGENT); }
; __device__ __forceinline__ unsigned xb_add(unsigned* p, unsigned v) { return __hip_atomic_fetch_add(p, v, __ATOMIC_RELAXED, __HIP_MEMORY_SCOPE_AGENT); }
; #define XB_SPIN(cond, bar) do { unsigned _sp = 0; while (cond) { \
;     if ((++_sp & 255u) == 0u) { if (xb_ld(&(bar)[XB_TMO])) break; if (_sp > XB_SPIN_CAP) { atomicAdd(&(bar)[XB_TMO], 1u); break; } } } } while (0)
; __device__ __forceinline__ void xcd_barrier(unsigned* barw, volatile LAS unsigned* stw, const int wv) {
;     ...
;         const unsigned old = xb_add(&bar[XB_XSUB(b.x)], 1u);
;         const unsigned gen = old / nloc;
;         if (old + 1u == (gen + 1u) * nloc) {
;             __builtin_amdgcn_fence(__ATOMIC_RELEASE, "agent");
;             asm volatile("s_waitcnt vmcnt(0)" ::: "memory");
;             const unsigned og = xb_add(&bar[XB_TOP], 1u);
;             const unsigned tg = og / nx;
;             if (og + 1u == (tg + 1u) * nx) xb_add(&bar[XB_TOPGEN], 1u);
;             else XB_SPIN(xb_ld(&bar[XB_TOPGEN]) == tg, bar);
;             __builtin_amdgcn_fence(__ATOMIC_ACQUIRE, "agent");
;             xb_add(&bar[XB_XGEN(b.x)], 1u);
;             asm volatile("s_waitcnt vmcnt(0)" ::: "memory");
;         } else {
;             XB_SPIN(xb_ld(&bar[XB_XGEN(b.x)]) == gen, bar);
.LBB0_1101:
	s_or_b64 exec, exec, s[10:11]
	v_cvt_f32_u32_e32 v4, v2
	s_waitcnt vmcnt(0)
	v_readfirstlane_b32 s8, v3
	v_sub_u32_e32 v3, 0, v2
	v_rcp_iflag_f32_e32 v4, v4
	v_add_u32_e32 v5, s8, v1
	v_mul_f32_e32 v4, 0x4f7ffffe, v4
	v_cvt_u32_f32_e32 v4, v4
	v_mul_lo_u32 v1, v3, v4
	v_mul_hi_u32 v1, v4, v1
	v_add_u32_e32 v1, v4, v1
	v_mul_hi_u32 v1, v5, v1
	v_mul_lo_u32 v3, v1, v2
	v_sub_u32_e32 v3, v5, v3
	v_add_u32_e32 v4, 1, v1
	v_cmp_ge_u32_e32 vcc, v3, v2
	s_nop 1
	v_cndmask_b32_e32 v1, v1, v4, vcc
	v_sub_u32_e32 v4, v3, v2
	v_cndmask_b32_e32 v3, v3, v4, vcc
	v_add_u32_e32 v4, 1, v1
	v_cmp_ge_u32_e32 vcc, v3, v2
	v_add_u32_e32 v3, 1, v5
	s_nop 0
	v_cndmask_b32_e32 v1, v1, v4, vcc
	v_mul_lo_u32 v4, v2, v1
	v_add_u32_e32 v2, v4, v2
	v_cmp_ne_u32_e32 vcc, v3, v2
	s_and_saveexec_b64 s[8:9], vcc
	s_xor_b64 s[8:9], exec, s[8:9]
	s_cbranch_execz .LBB0_1115
	s_waitcnt lgkmcnt(0)
	buffer_inv sc1
	v_mov_b32_e32 v0, 0x3100
	global_load_dword v0, v0, s[2:3] offset:1024 sc1
	s_add_u32 s12, s2, 0x3500
	s_addc_u32 s13, s3, 0
	s_waitcnt vmcnt(0)
	v_cmp_eq_u32_e32 vcc, v0, v1
	s_and_saveexec_b64 s[10:11], vcc
	s_cbranch_execz .LBB0_1114
	s_mov_b32 s24, 1
	s_mov_b64 s[14:15], 0
	v_mov_b32_e32 v0, 0
	s_branch .LBB0_1105

; __device__ __forceinline__ unsigned xb_ld(unsigned* p)              { return __hip_atomic_load(p, __ATOMIC_RELAXED, __HIP_MEMORY_SCOPE_AGENT); }
; __device__ __forceinline__ unsigned xb_add(unsigned* p, unsigned v) { return __hip_atomic_fetch_add(p, v, __ATOMIC_RELAXED, __HIP_MEMORY_SCOPE_AGENT); }
; #define XB_SPIN(cond, bar) do { unsigned _sp = 0; while (cond) { \
;     if ((++_sp & 255u) == 0u) { if (xb_ld(&(bar)[XB_TMO])) break; if (_sp > XB_SPIN_CAP) { atomicAdd(&(bar)[XB_TMO], 1u); break; } } } } while (0)
; __device__ __forceinline__ void xcd_barrier(unsigned* barw, volatile LAS unsigned* stw, const int wv) {
;     ...
;         if (old + 1u == (gen + 1u) * nloc) {
;             __builtin_amdgcn_fence(__ATOMIC_RELEASE, "agent");
;             asm volatile("s_waitcnt vmcnt(0)" ::: "memory");
;             const unsigned og = xb_add(&bar[XB_TOP], 1u);
;             const unsigned tg = og / nx;
;             if (og + 1u == (tg + 1u) * nx) xb_add(&bar[XB_TOPGEN], 1u);
;             else XB_SPIN(xb_ld(&bar[XB_TOPGEN]) == tg, bar);
.LBB0_1115:
	s_andn2_saveexec_b64 s[8:9], s[8:9]
	s_cbranch_execz .LBB0_1135
	s_mov_b64 s[8:9], exec
	buffer_wbl2 sc1
	buffer_inv sc1
	s_waitcnt lgkmcnt(0)
	s_waitcnt vmcnt(0)
	v_mbcnt_lo_u32_b32 v1, s8, 0
	v_mbcnt_hi_u32_b32 v1, s9, v1
	v_cmp_eq_u32_e32 vcc, 0, v1
	s_and_saveexec_b64 s[10:11], vcc
	s_cbranch_execz .LBB0_1118
	s_bcnt1_i32_b64 s8, s[8:9]
	v_mov_b32_e32 v2, 0x3000
	v_mov_b32_e32 v3, s8
	global_atomic_add v2, v2, v3, s[2:3] offset:1024 sc0

; __device__ __forceinline__ unsigned xb_ld(unsigned* p)              { return __hip_atomic_load(p, __ATOMIC_RELAXED, __HIP_MEMORY_SCOPE_AGENT); }
; __device__ __forceinline__ unsigned xb_add(unsigned* p, unsigned v) { return __hip_atomic_fetch_add(p, v, __ATOMIC_RELAXED, __HIP_MEMORY_SCOPE_AGENT); }
; #define XB_SPIN(cond, bar) do { unsigned _sp = 0; while (cond) { \
;     if ((++_sp & 255u) == 0u) { if (xb_ld(&(bar)[XB_TMO])) break; if (_sp > XB_SPIN_CAP) { atomicAdd(&(bar)[XB_TMO], 1u); break; } } } } while (0)
; __device__ __forceinline__ void xcd_barrier(unsigned* barw, volatile LAS unsigned* stw, const int wv) {
;     ...
;             else XB_SPIN(xb_ld(&bar[XB_TOPGEN]) == tg, bar);
;             __builtin_amdgcn_fence(__ATOMIC_ACQUIRE, "agent");
;             xb_add(&bar[XB_XGEN(b.x)], 1u);
;             asm volatile("s_waitcnt vmcnt(0)" ::: "memory");
.LBB0_1132:
	s_or_b64 exec, exec, s[2:3]
	s_mov_b64 s[2:3], exec
	v_mbcnt_lo_u32_b32 v0, s2, 0
	v_mbcnt_hi_u32_b32 v0, s3, v0
	v_cmp_eq_u32_e32 vcc, 0, v0
	s_waitcnt vmcnt(0)
	s_and_saveexec_b64 s[4:5], vcc
	s_cbranch_execz .LBB0_1134
